# GEMM k-loops: LDS-DMA issue interleaved between MFMAs (saddr form), lgkmcnt(6), tail loop
# speedup vs baseline: 1.0303x; 1.0303x over previous
.LBB0_171:
	s_add_u32 s74, s74, s50
	s_addc_u32 s75, s75, s51
	s_add_u32 s72, s72, s60
	s_addc_u32 s73, s73, s61
	v_mov_b32_e32 v128, 0
	v_mov_b32_e32 v129, 0
	v_mov_b32_e32 v130, 0
	v_mov_b32_e32 v131, 0
	v_mov_b32_e32 v132, 0
	v_mov_b32_e32 v133, 0
	v_mov_b32_e32 v134, 0
	v_mov_b32_e32 v135, 0
	v_mov_b32_e32 v136, 0
	v_mov_b32_e32 v137, 0
	v_mov_b32_e32 v138, 0
	v_mov_b32_e32 v139, 0
	v_mov_b32_e32 v140, 0
	v_mov_b32_e32 v141, 0
	v_mov_b32_e32 v142, 0
	v_mov_b32_e32 v143, 0
	v_mov_b32_e32 v144, 0
	v_mov_b32_e32 v145, 0
	v_mov_b32_e32 v146, 0
	v_mov_b32_e32 v147, 0
	v_mov_b32_e32 v148, 0
	v_mov_b32_e32 v149, 0
	v_mov_b32_e32 v150, 0
	v_mov_b32_e32 v151, 0
.Lgemm_g1_main:
	s_add_i32 s18, s11, 0
	v_add_u32_e32 v182, s18, v178
	v_add_u32_e32 v152, v182, v180
	ds_read_b128 v[172:175], v152
	ds_read_b128 v[168:171], v152 offset:2048
	ds_read_b128 v[156:159], v152 offset:4096
	ds_read_b128 v[152:155], v152 offset:6144
	v_add_u32_e32 v183, s18, v179
	v_add_u32_e32 v160, v183, v180
	ds_read_b128 v[164:167], v160 offset:16384
	ds_read_b128 v[160:163], v160 offset:18432
	s_add_i32 s18, s0, s10
	s_mov_b32 m0, s18
	v_mfma_f32_32x32x16_bf16 v[112:127], v[136:139], v[148:151], v[112:127]
	global_load_lds_dwordx4 v176, s[74:75]
	s_add_u32 s98, s74, 0x1000
	s_addc_u32 s99, s75, 0
	s_add_i32 m0, s18, 0x1000
	v_mfma_f32_32x32x16_bf16 v[96:111], v[132:135], v[148:151], v[96:111]
	v_mfma_f32_32x32x16_bf16 v[80:95], v[136:139], v[144:147], v[80:95]
	global_load_lds_dwordx4 v176, s[98:99]
	s_add_u32 s100, s74, 0x2000
	s_addc_u32 s101, s75, 0
	s_add_i32 m0, s18, 0x2000
	v_mfma_f32_32x32x16_bf16 v[64:79], v[132:135], v[144:147], v[64:79]
	v_mfma_f32_32x32x16_bf16 v[48:63], v[136:139], v[140:143], v[48:63]
	global_load_lds_dwordx4 v176, s[100:101]
	s_add_u32 s98, s74, 0x3000
	s_addc_u32 s99, s75, 0
	s_add_i32 m0, s18, 0x3000
	v_mfma_f32_32x32x16_bf16 v[32:47], v[132:135], v[140:143], v[32:47]
	v_mfma_f32_32x32x16_bf16 v[16:31], v[136:139], v[128:131], v[16:31]
	global_load_lds_dwordx4 v176, s[98:99]
	v_mfma_f32_32x32x16_bf16 v[0:15], v[132:135], v[128:131], v[0:15]
	v_add_u32_e32 v128, v182, v181
	ds_read_b128 v[148:151], v128
	ds_read_b128 v[144:147], v128 offset:2048
	ds_read_b128 v[140:143], v128 offset:4096
	ds_read_b128 v[128:131], v128 offset:6144
	v_add_u32_e32 v132, v183, v181
	ds_read_b128 v[136:139], v132 offset:16384
	ds_read_b128 v[132:135], v132 offset:18432
	s_add_i32 m0, s18, 0x4000
	s_add_u32 s100, s72, 0x1000
	s_addc_u32 s101, s73, 0
	s_waitcnt lgkmcnt(6)
	v_mfma_f32_32x32x16_bf16 v[112:127], v[164:167], v[172:175], v[112:127]
	global_load_lds_dwordx4 v176, s[72:73]
	s_add_i32 m0, s18, 0x5000
	v_mfma_f32_32x32x16_bf16 v[96:111], v[160:163], v[172:175], v[96:111]
	v_mfma_f32_32x32x16_bf16 v[80:95], v[164:167], v[168:171], v[80:95]
	global_load_lds_dwordx4 v176, s[100:101]
	v_mfma_f32_32x32x16_bf16 v[64:79], v[160:163], v[168:171], v[64:79]
	v_mfma_f32_32x32x16_bf16 v[48:63], v[164:167], v[156:159], v[48:63]
	v_mfma_f32_32x32x16_bf16 v[32:47], v[160:163], v[156:159], v[32:47]
	v_mfma_f32_32x32x16_bf16 v[16:31], v[164:167], v[152:155], v[16:31]
	v_mfma_f32_32x32x16_bf16 v[0:15], v[160:163], v[152:155], v[0:15]
	s_add_u32 s74, s74, 0x80000
	s_addc_u32 s75, s75, 0
	s_add_u32 s72, s72, 0x5e000
	s_addc_u32 s73, s73, 0
	s_add_i32 s18, s10, 0x6000
	s_cmpk_lg_u32 s10, 0xc000
	s_cselect_b32 s10, s18, 0
	s_add_i32 s18, s11, 0x6000
	s_cmpk_lg_u32 s11, 0xc000
	s_cselect_b32 s11, s18, 0
	s_add_i32 s1, s1, 1
	s_waitcnt vmcnt(6) lgkmcnt(0)
	s_barrier
	s_cmp_lg_u32 s1, 62
	s_cbranch_scc1 .Lgemm_g1_main
.Lgemm_g1_tail:
	s_add_i32 s18, s11, 0
	v_add_u32_e32 v182, s18, v178
	v_add_u32_e32 v152, v182, v180
	ds_read_b128 v[172:175], v152
	ds_read_b128 v[168:171], v152 offset:2048
	ds_read_b128 v[156:159], v152 offset:4096
	ds_read_b128 v[152:155], v152 offset:6144
	v_add_u32_e32 v183, s18, v179
	v_add_u32_e32 v160, v183, v180
	ds_read_b128 v[164:167], v160 offset:16384
	ds_read_b128 v[160:163], v160 offset:18432
	v_mfma_f32_32x32x16_bf16 v[112:127], v[136:139], v[148:151], v[112:127]
	v_mfma_f32_32x32x16_bf16 v[96:111], v[132:135], v[148:151], v[96:111]
	v_mfma_f32_32x32x16_bf16 v[80:95], v[136:139], v[144:147], v[80:95]
	v_mfma_f32_32x32x16_bf16 v[64:79], v[132:135], v[144:147], v[64:79]
	v_mfma_f32_32x32x16_bf16 v[48:63], v[136:139], v[140:143], v[48:63]
	v_mfma_f32_32x32x16_bf16 v[32:47], v[132:135], v[140:143], v[32:47]
	v_mfma_f32_32x32x16_bf16 v[16:31], v[136:139], v[128:131], v[16:31]
	v_mfma_f32_32x32x16_bf16 v[0:15], v[132:135], v[128:131], v[0:15]
	v_add_u32_e32 v128, v182, v181
	ds_read_b128 v[148:151], v128
	ds_read_b128 v[144:147], v128 offset:2048
	ds_read_b128 v[140:143], v128 offset:4096
	ds_read_b128 v[128:131], v128 offset:6144
	v_add_u32_e32 v132, v183, v181
	ds_read_b128 v[136:139], v132 offset:16384
	ds_read_b128 v[132:135], v132 offset:18432
	s_waitcnt lgkmcnt(6)
	v_mfma_f32_32x32x16_bf16 v[112:127], v[164:167], v[172:175], v[112:127]
	v_mfma_f32_32x32x16_bf16 v[96:111], v[160:163], v[172:175], v[96:111]
	v_mfma_f32_32x32x16_bf16 v[80:95], v[164:167], v[168:171], v[80:95]
	v_mfma_f32_32x32x16_bf16 v[64:79], v[160:163], v[168:171], v[64:79]
	v_mfma_f32_32x32x16_bf16 v[48:63], v[164:167], v[156:159], v[48:63]
	v_mfma_f32_32x32x16_bf16 v[32:47], v[160:163], v[156:159], v[32:47]
	v_mfma_f32_32x32x16_bf16 v[16:31], v[164:167], v[152:155], v[16:31]
	v_mfma_f32_32x32x16_bf16 v[0:15], v[160:163], v[152:155], v[0:15]
	s_add_i32 s18, s11, 0x6000
	s_cmpk_lg_u32 s11, 0xc000
	s_cselect_b32 s11, s18, 0
	s_add_i32 s1, s1, 1
	s_waitcnt vmcnt(0) lgkmcnt(0)
	s_barrier
	s_cmp_lg_u32 s1, 64
	s_cbranch_scc1 .Lgemm_g1_tail
	s_branch .LBB0_179

.LBB0_224:
	s_add_u32 s68, s68, s50
	s_addc_u32 s69, s69, s51
	s_add_u32 s70, s70, s60
	s_addc_u32 s71, s71, s61
	v_mov_b32_e32 v128, 0
	v_mov_b32_e32 v129, 0
	v_mov_b32_e32 v130, 0
	v_mov_b32_e32 v131, 0
	v_mov_b32_e32 v132, 0
	v_mov_b32_e32 v133, 0
	v_mov_b32_e32 v134, 0
	v_mov_b32_e32 v135, 0
	v_mov_b32_e32 v136, 0
	v_mov_b32_e32 v137, 0
	v_mov_b32_e32 v138, 0
	v_mov_b32_e32 v139, 0
	v_mov_b32_e32 v140, 0
	v_mov_b32_e32 v141, 0
	v_mov_b32_e32 v142, 0
	v_mov_b32_e32 v143, 0
	v_mov_b32_e32 v144, 0
	v_mov_b32_e32 v145, 0
	v_mov_b32_e32 v146, 0
	v_mov_b32_e32 v147, 0
	v_mov_b32_e32 v148, 0
	v_mov_b32_e32 v149, 0
	v_mov_b32_e32 v150, 0
	v_mov_b32_e32 v151, 0
.Lgemm_g2_main:
	s_add_i32 s18, s11, 0
	v_add_u32_e32 v182, s18, v178
	v_add_u32_e32 v152, v182, v180
	ds_read_b128 v[172:175], v152
	ds_read_b128 v[168:171], v152 offset:2048
	ds_read_b128 v[156:159], v152 offset:4096
	ds_read_b128 v[152:155], v152 offset:6144
	v_add_u32_e32 v183, s18, v179
	v_add_u32_e32 v160, v183, v180
	ds_read_b128 v[164:167], v160 offset:16384
	ds_read_b128 v[160:163], v160 offset:18432
	s_add_i32 s18, s0, s10
	s_mov_b32 m0, s18
	v_mfma_f32_32x32x16_bf16 v[112:127], v[148:151], v[132:135], v[112:127]
	global_load_lds_dwordx4 v176, s[68:69]
	s_add_u32 s98, s68, 0x1000
	s_addc_u32 s99, s69, 0
	s_add_i32 m0, s18, 0x1000
	v_mfma_f32_32x32x16_bf16 v[96:111], v[148:151], v[136:139], v[96:111]
	v_mfma_f32_32x32x16_bf16 v[80:95], v[144:147], v[132:135], v[80:95]
	global_load_lds_dwordx4 v176, s[98:99]
	s_add_u32 s100, s68, 0x2000
	s_addc_u32 s101, s69, 0
	s_add_i32 m0, s18, 0x2000
	v_mfma_f32_32x32x16_bf16 v[64:79], v[144:147], v[136:139], v[64:79]
	v_mfma_f32_32x32x16_bf16 v[48:63], v[140:143], v[132:135], v[48:63]
	global_load_lds_dwordx4 v176, s[100:101]
	s_add_u32 s98, s68, 0x3000
	s_addc_u32 s99, s69, 0
	s_add_i32 m0, s18, 0x3000
	v_mfma_f32_32x32x16_bf16 v[32:47], v[140:143], v[136:139], v[32:47]
	v_mfma_f32_32x32x16_bf16 v[16:31], v[128:131], v[132:135], v[16:31]
	global_load_lds_dwordx4 v176, s[98:99]
	v_mfma_f32_32x32x16_bf16 v[0:15], v[128:131], v[136:139], v[0:15]
	v_add_u32_e32 v128, v182, v181
	ds_read_b128 v[148:151], v128
	ds_read_b128 v[144:147], v128 offset:2048
	ds_read_b128 v[140:143], v128 offset:4096
	ds_read_b128 v[128:131], v128 offset:6144
	v_add_u32_e32 v136, v183, v181
	ds_read_b128 v[132:135], v136 offset:16384
	ds_read_b128 v[136:139], v136 offset:18432
	s_add_i32 m0, s18, 0x4000
	s_add_u32 s100, s70, 0x1000
	s_addc_u32 s101, s71, 0
	s_waitcnt lgkmcnt(6)
	v_mfma_f32_32x32x16_bf16 v[112:127], v[172:175], v[164:167], v[112:127]
	global_load_lds_dwordx4 v176, s[70:71]
	s_add_i32 m0, s18, 0x5000
	v_mfma_f32_32x32x16_bf16 v[96:111], v[172:175], v[160:163], v[96:111]
	v_mfma_f32_32x32x16_bf16 v[80:95], v[168:171], v[164:167], v[80:95]
	global_load_lds_dwordx4 v176, s[100:101]
	v_mfma_f32_32x32x16_bf16 v[64:79], v[168:171], v[160:163], v[64:79]
	v_mfma_f32_32x32x16_bf16 v[48:63], v[156:159], v[164:167], v[48:63]
	v_mfma_f32_32x32x16_bf16 v[32:47], v[156:159], v[160:163], v[32:47]
	v_mfma_f32_32x32x16_bf16 v[16:31], v[152:155], v[164:167], v[16:31]
	v_mfma_f32_32x32x16_bf16 v[0:15], v[152:155], v[160:163], v[0:15]
	s_add_u32 s68, s68, 0x80000
	s_addc_u32 s69, s69, 0
	s_add_u32 s70, s70, 0x5e000
	s_addc_u32 s71, s71, 0
	s_add_i32 s18, s10, 0x6000
	s_cmpk_lg_u32 s10, 0xc000
	s_cselect_b32 s10, s18, 0
	s_add_i32 s18, s11, 0x6000
	s_cmpk_lg_u32 s11, 0xc000
	s_cselect_b32 s11, s18, 0
	s_add_i32 s1, s1, 1
	s_waitcnt vmcnt(6) lgkmcnt(0)
	s_barrier
	s_cmp_lg_u32 s1, 62
	s_cbranch_scc1 .Lgemm_g2_main
.Lgemm_g2_tail:
	s_add_i32 s18, s11, 0
	v_add_u32_e32 v182, s18, v178
	v_add_u32_e32 v152, v182, v180
	ds_read_b128 v[172:175], v152
	ds_read_b128 v[168:171], v152 offset:2048
	ds_read_b128 v[156:159], v152 offset:4096
	ds_read_b128 v[152:155], v152 offset:6144
	v_add_u32_e32 v183, s18, v179
	v_add_u32_e32 v160, v183, v180
	ds_read_b128 v[164:167], v160 offset:16384
	ds_read_b128 v[160:163], v160 offset:18432
	v_mfma_f32_32x32x16_bf16 v[112:127], v[148:151], v[132:135], v[112:127]
	v_mfma_f32_32x32x16_bf16 v[96:111], v[148:151], v[136:139], v[96:111]
	v_mfma_f32_32x32x16_bf16 v[80:95], v[144:147], v[132:135], v[80:95]
	v_mfma_f32_32x32x16_bf16 v[64:79], v[144:147], v[136:139], v[64:79]
	v_mfma_f32_32x32x16_bf16 v[48:63], v[140:143], v[132:135], v[48:63]
	v_mfma_f32_32x32x16_bf16 v[32:47], v[140:143], v[136:139], v[32:47]
	v_mfma_f32_32x32x16_bf16 v[16:31], v[128:131], v[132:135], v[16:31]
	v_mfma_f32_32x32x16_bf16 v[0:15], v[128:131], v[136:139], v[0:15]
	v_add_u32_e32 v128, v182, v181
	ds_read_b128 v[148:151], v128
	ds_read_b128 v[144:147], v128 offset:2048
	ds_read_b128 v[140:143], v128 offset:4096
	ds_read_b128 v[128:131], v128 offset:6144
	v_add_u32_e32 v136, v183, v181
	ds_read_b128 v[132:135], v136 offset:16384
	ds_read_b128 v[136:139], v136 offset:18432
	s_waitcnt lgkmcnt(6)
	v_mfma_f32_32x32x16_bf16 v[112:127], v[172:175], v[164:167], v[112:127]
	v_mfma_f32_32x32x16_bf16 v[96:111], v[172:175], v[160:163], v[96:111]
	v_mfma_f32_32x32x16_bf16 v[80:95], v[168:171], v[164:167], v[80:95]
	v_mfma_f32_32x32x16_bf16 v[64:79], v[168:171], v[160:163], v[64:79]
	v_mfma_f32_32x32x16_bf16 v[48:63], v[156:159], v[164:167], v[48:63]
	v_mfma_f32_32x32x16_bf16 v[32:47], v[156:159], v[160:163], v[32:47]
	v_mfma_f32_32x32x16_bf16 v[16:31], v[152:155], v[164:167], v[16:31]
	v_mfma_f32_32x32x16_bf16 v[0:15], v[152:155], v[160:163], v[0:15]
	s_add_i32 s18, s11, 0x6000
	s_cmpk_lg_u32 s11, 0xc000
	s_cselect_b32 s11, s18, 0
	s_add_i32 s1, s1, 1
	s_waitcnt vmcnt(0) lgkmcnt(0)
	s_barrier
	s_cmp_lg_u32 s1, 64
	s_cbranch_scc1 .Lgemm_g2_tail
	s_branch .LBB0_165

.LBB0_291:
	s_add_u32 s6, s6, s56
	s_addc_u32 s7, s7, s57
	s_add_u32 s4, s4, s64
	s_addc_u32 s5, s5, s65
	v_mov_b32_e32 v128, 0
	v_mov_b32_e32 v129, 0
	v_mov_b32_e32 v130, 0
	v_mov_b32_e32 v131, 0
	v_mov_b32_e32 v132, 0
	v_mov_b32_e32 v133, 0
	v_mov_b32_e32 v134, 0
	v_mov_b32_e32 v135, 0
	v_mov_b32_e32 v136, 0
	v_mov_b32_e32 v137, 0
	v_mov_b32_e32 v138, 0
	v_mov_b32_e32 v139, 0
	v_mov_b32_e32 v140, 0
	v_mov_b32_e32 v141, 0
	v_mov_b32_e32 v142, 0
	v_mov_b32_e32 v143, 0
	v_mov_b32_e32 v144, 0
	v_mov_b32_e32 v145, 0
	v_mov_b32_e32 v146, 0
	v_mov_b32_e32 v147, 0
	v_mov_b32_e32 v148, 0
	v_mov_b32_e32 v149, 0
	v_mov_b32_e32 v150, 0
	v_mov_b32_e32 v151, 0
.Lgemm_g3_main:
	s_add_i32 s79, s37, 0
	v_add_u32_e32 v182, s79, v178
	v_add_u32_e32 v152, v182, v180
	ds_read_b128 v[172:175], v152
	ds_read_b128 v[168:171], v152 offset:2048
	ds_read_b128 v[156:159], v152 offset:4096
	ds_read_b128 v[152:155], v152 offset:6144
	v_add_u32_e32 v183, s79, v179
	v_add_u32_e32 v160, v183, v180
	ds_read_b128 v[164:167], v160 offset:16384
	ds_read_b128 v[160:163], v160 offset:18432
	s_add_i32 s8, s22, s36
	s_mov_b32 m0, s8
	v_mfma_f32_32x32x16_bf16 v[112:127], v[148:151], v[132:135], v[112:127]
	global_load_lds_dwordx4 v176, s[6:7]
	s_add_u32 s98, s6, 0x1000
	s_addc_u32 s99, s7, 0
	s_add_i32 m0, s8, 0x1000
	v_mfma_f32_32x32x16_bf16 v[96:111], v[148:151], v[136:139], v[96:111]
	v_mfma_f32_32x32x16_bf16 v[80:95], v[144:147], v[132:135], v[80:95]
	global_load_lds_dwordx4 v176, s[98:99]
	s_add_u32 s100, s6, 0x2000
	s_addc_u32 s101, s7, 0
	s_add_i32 m0, s8, 0x2000
	v_mfma_f32_32x32x16_bf16 v[64:79], v[144:147], v[136:139], v[64:79]
	v_mfma_f32_32x32x16_bf16 v[48:63], v[140:143], v[132:135], v[48:63]
	global_load_lds_dwordx4 v176, s[100:101]
	s_add_u32 s98, s6, 0x3000
	s_addc_u32 s99, s7, 0
	s_add_i32 m0, s8, 0x3000
	v_mfma_f32_32x32x16_bf16 v[32:47], v[140:143], v[136:139], v[32:47]
	v_mfma_f32_32x32x16_bf16 v[16:31], v[128:131], v[132:135], v[16:31]
	global_load_lds_dwordx4 v176, s[98:99]
	v_mfma_f32_32x32x16_bf16 v[0:15], v[128:131], v[136:139], v[0:15]
	v_add_u32_e32 v128, v182, v181
	ds_read_b128 v[148:151], v128
	ds_read_b128 v[144:147], v128 offset:2048
	ds_read_b128 v[140:143], v128 offset:4096
	ds_read_b128 v[128:131], v128 offset:6144
	v_add_u32_e32 v136, v183, v181
	ds_read_b128 v[132:135], v136 offset:16384
	ds_read_b128 v[136:139], v136 offset:18432
	s_add_i32 m0, s8, 0x4000
	s_add_u32 s100, s4, 0x1000
	s_addc_u32 s101, s5, 0
	s_waitcnt lgkmcnt(6)
	v_mfma_f32_32x32x16_bf16 v[112:127], v[172:175], v[164:167], v[112:127]
	global_load_lds_dwordx4 v176, s[4:5]
	s_add_i32 m0, s8, 0x5000
	v_mfma_f32_32x32x16_bf16 v[96:111], v[172:175], v[160:163], v[96:111]
	v_mfma_f32_32x32x16_bf16 v[80:95], v[168:171], v[164:167], v[80:95]
	global_load_lds_dwordx4 v176, s[100:101]
	v_mfma_f32_32x32x16_bf16 v[64:79], v[168:171], v[160:163], v[64:79]
	v_mfma_f32_32x32x16_bf16 v[48:63], v[156:159], v[164:167], v[48:63]
	v_mfma_f32_32x32x16_bf16 v[32:47], v[156:159], v[160:163], v[32:47]
	v_mfma_f32_32x32x16_bf16 v[16:31], v[152:155], v[164:167], v[16:31]
	v_mfma_f32_32x32x16_bf16 v[0:15], v[152:155], v[160:163], v[0:15]
	s_add_u32 s6, s6, 0x80000
	s_addc_u32 s7, s7, 0
	s_add_u32 s4, s4, 0x20000
	s_addc_u32 s5, s5, 0
	s_add_i32 s8, s36, 0x6000
	s_cmpk_lg_u32 s36, 0xc000
	s_cselect_b32 s36, s8, 0
	s_add_i32 s8, s37, 0x6000
	s_cmpk_lg_u32 s37, 0xc000
	s_cselect_b32 s37, s8, 0
	s_add_i32 s33, s33, 1
	s_waitcnt vmcnt(6) lgkmcnt(0)
	s_barrier
	s_cmp_lg_u32 s33, 6
	s_cbranch_scc1 .Lgemm_g3_main
.Lgemm_g3_tail:
	s_add_i32 s79, s37, 0
	v_add_u32_e32 v182, s79, v178
	v_add_u32_e32 v152, v182, v180
	ds_read_b128 v[172:175], v152
	ds_read_b128 v[168:171], v152 offset:2048
	ds_read_b128 v[156:159], v152 offset:4096
	ds_read_b128 v[152:155], v152 offset:6144
	v_add_u32_e32 v183, s79, v179
	v_add_u32_e32 v160, v183, v180
	ds_read_b128 v[164:167], v160 offset:16384
	ds_read_b128 v[160:163], v160 offset:18432
	v_mfma_f32_32x32x16_bf16 v[112:127], v[148:151], v[132:135], v[112:127]
	v_mfma_f32_32x32x16_bf16 v[96:111], v[148:151], v[136:139], v[96:111]
	v_mfma_f32_32x32x16_bf16 v[80:95], v[144:147], v[132:135], v[80:95]
	v_mfma_f32_32x32x16_bf16 v[64:79], v[144:147], v[136:139], v[64:79]
	v_mfma_f32_32x32x16_bf16 v[48:63], v[140:143], v[132:135], v[48:63]
	v_mfma_f32_32x32x16_bf16 v[32:47], v[140:143], v[136:139], v[32:47]
	v_mfma_f32_32x32x16_bf16 v[16:31], v[128:131], v[132:135], v[16:31]
	v_mfma_f32_32x32x16_bf16 v[0:15], v[128:131], v[136:139], v[0:15]
	v_add_u32_e32 v128, v182, v181
	ds_read_b128 v[148:151], v128
	ds_read_b128 v[144:147], v128 offset:2048
	ds_read_b128 v[140:143], v128 offset:4096
	ds_read_b128 v[128:131], v128 offset:6144
	v_add_u32_e32 v136, v183, v181
	ds_read_b128 v[132:135], v136 offset:16384
	ds_read_b128 v[136:139], v136 offset:18432
	s_waitcnt lgkmcnt(6)
	v_mfma_f32_32x32x16_bf16 v[112:127], v[172:175], v[164:167], v[112:127]
	v_mfma_f32_32x32x16_bf16 v[96:111], v[172:175], v[160:163], v[96:111]
	v_mfma_f32_32x32x16_bf16 v[80:95], v[168:171], v[164:167], v[80:95]
	v_mfma_f32_32x32x16_bf16 v[64:79], v[168:171], v[160:163], v[64:79]
	v_mfma_f32_32x32x16_bf16 v[48:63], v[156:159], v[164:167], v[48:63]
	v_mfma_f32_32x32x16_bf16 v[32:47], v[156:159], v[160:163], v[32:47]
	v_mfma_f32_32x32x16_bf16 v[16:31], v[152:155], v[164:167], v[16:31]
	v_mfma_f32_32x32x16_bf16 v[0:15], v[152:155], v[160:163], v[0:15]
	s_add_i32 s8, s37, 0x6000
	s_cmpk_lg_u32 s37, 0xc000
	s_cselect_b32 s37, s8, 0
	s_add_i32 s33, s33, 1
	s_waitcnt vmcnt(0) lgkmcnt(0)
	s_barrier
	s_cmp_lg_u32 s33, 8
	s_cbranch_scc1 .Lgemm_g3_tail
	s_branch .LBB0_299

.Lgemm_g4_main:
	s_add_i32 s33, s22, 0
	v_add_u32_e32 v182, s33, v178
	v_add_u32_e32 v152, v182, v180
	ds_read_b128 v[172:175], v152
	ds_read_b128 v[168:171], v152 offset:2048
	ds_read_b128 v[156:159], v152 offset:4096
	ds_read_b128 v[152:155], v152 offset:6144
	v_add_u32_e32 v183, s33, v179
	v_add_u32_e32 v160, v183, v180
	ds_read_b128 v[164:167], v160 offset:16384
	ds_read_b128 v[160:163], v160 offset:18432
	s_add_i32 s8, s0, s11
	s_mov_b32 m0, s8
	v_mfma_f32_32x32x16_bf16 v[112:127], v[144:147], v[148:151], v[112:127]
	global_load_lds_dwordx4 v176, s[6:7]
	s_add_u32 s98, s6, 0x1000
	s_addc_u32 s99, s7, 0
	s_add_i32 m0, s8, 0x1000
	v_mfma_f32_32x32x16_bf16 v[96:111], v[132:135], v[148:151], v[96:111]
	v_mfma_f32_32x32x16_bf16 v[80:95], v[144:147], v[140:143], v[80:95]
	global_load_lds_dwordx4 v176, s[98:99]
	s_add_u32 s100, s6, 0x2000
	s_addc_u32 s101, s7, 0
	s_add_i32 m0, s8, 0x2000
	v_mfma_f32_32x32x16_bf16 v[64:79], v[132:135], v[140:143], v[64:79]
	v_mfma_f32_32x32x16_bf16 v[48:63], v[144:147], v[136:139], v[48:63]
	global_load_lds_dwordx4 v176, s[100:101]
	s_add_u32 s98, s6, 0x3000
	s_addc_u32 s99, s7, 0
	s_add_i32 m0, s8, 0x3000
	v_mfma_f32_32x32x16_bf16 v[32:47], v[132:135], v[136:139], v[32:47]
	v_mfma_f32_32x32x16_bf16 v[16:31], v[144:147], v[128:131], v[16:31]
	global_load_lds_dwordx4 v176, s[98:99]
	v_mfma_f32_32x32x16_bf16 v[0:15], v[132:135], v[128:131], v[0:15]
	v_add_u32_e32 v128, v182, v181
	ds_read_b128 v[148:151], v128
	ds_read_b128 v[140:143], v128 offset:2048
	ds_read_b128 v[136:139], v128 offset:4096
	ds_read_b128 v[128:131], v128 offset:6144
	v_add_u32_e32 v132, v183, v181
	ds_read_b128 v[144:147], v132 offset:16384
	ds_read_b128 v[132:135], v132 offset:18432
	s_add_i32 m0, s8, 0x4000
	s_add_u32 s100, s4, 0x1000
	s_addc_u32 s101, s5, 0
	s_waitcnt lgkmcnt(6)
	v_mfma_f32_32x32x16_bf16 v[112:127], v[164:167], v[172:175], v[112:127]
	global_load_lds_dwordx4 v176, s[4:5]
	s_add_i32 m0, s8, 0x5000
	v_mfma_f32_32x32x16_bf16 v[96:111], v[160:163], v[172:175], v[96:111]
	v_mfma_f32_32x32x16_bf16 v[80:95], v[164:167], v[168:171], v[80:95]
	global_load_lds_dwordx4 v176, s[100:101]
	v_mfma_f32_32x32x16_bf16 v[64:79], v[160:163], v[168:171], v[64:79]
	v_mfma_f32_32x32x16_bf16 v[48:63], v[164:167], v[156:159], v[48:63]
	v_mfma_f32_32x32x16_bf16 v[32:47], v[160:163], v[156:159], v[32:47]
	v_mfma_f32_32x32x16_bf16 v[16:31], v[164:167], v[152:155], v[16:31]
	v_mfma_f32_32x32x16_bf16 v[0:15], v[160:163], v[152:155], v[0:15]
	s_add_u32 s6, s6, 0x80000
	s_addc_u32 s7, s7, 0
	s_add_u32 s4, s4, 0x20000
	s_addc_u32 s5, s5, 0
	s_add_i32 s8, s11, 0x6000
	s_cmpk_lg_u32 s11, 0xc000
	s_cselect_b32 s11, s8, 0
	s_add_i32 s8, s22, 0x6000
	s_cmpk_lg_u32 s22, 0xc000
	s_cselect_b32 s22, s8, 0
	s_add_i32 s1, s1, 1
	s_waitcnt vmcnt(6) lgkmcnt(0)
	s_barrier
	s_cmp_lg_u32 s1, 6
	s_cbranch_scc1 .Lgemm_g4_main
.Lgemm_g4_tail:
	s_add_i32 s33, s22, 0
	v_add_u32_e32 v182, s33, v178
	v_add_u32_e32 v152, v182, v180
	ds_read_b128 v[172:175], v152
	ds_read_b128 v[168:171], v152 offset:2048
	ds_read_b128 v[156:159], v152 offset:4096
	ds_read_b128 v[152:155], v152 offset:6144
	v_add_u32_e32 v183, s33, v179
	v_add_u32_e32 v160, v183, v180
	ds_read_b128 v[164:167], v160 offset:16384
	ds_read_b128 v[160:163], v160 offset:18432
	v_mfma_f32_32x32x16_bf16 v[112:127], v[144:147], v[148:151], v[112:127]
	v_mfma_f32_32x32x16_bf16 v[96:111], v[132:135], v[148:151], v[96:111]
	v_mfma_f32_32x32x16_bf16 v[80:95], v[144:147], v[140:143], v[80:95]
	v_mfma_f32_32x32x16_bf16 v[64:79], v[132:135], v[140:143], v[64:79]
	v_mfma_f32_32x32x16_bf16 v[48:63], v[144:147], v[136:139], v[48:63]
	v_mfma_f32_32x32x16_bf16 v[32:47], v[132:135], v[136:139], v[32:47]
	v_mfma_f32_32x32x16_bf16 v[16:31], v[144:147], v[128:131], v[16:31]
	v_mfma_f32_32x32x16_bf16 v[0:15], v[132:135], v[128:131], v[0:15]
	v_add_u32_e32 v128, v182, v181
	ds_read_b128 v[148:151], v128
	ds_read_b128 v[140:143], v128 offset:2048
	ds_read_b128 v[136:139], v128 offset:4096
	ds_read_b128 v[128:131], v128 offset:6144
	v_add_u32_e32 v132, v183, v181
	ds_read_b128 v[144:147], v132 offset:16384
	ds_read_b128 v[132:135], v132 offset:18432
	s_waitcnt lgkmcnt(6)
	v_mfma_f32_32x32x16_bf16 v[112:127], v[164:167], v[172:175], v[112:127]
	v_mfma_f32_32x32x16_bf16 v[96:111], v[160:163], v[172:175], v[96:111]
	v_mfma_f32_32x32x16_bf16 v[80:95], v[164:167], v[168:171], v[80:95]
	v_mfma_f32_32x32x16_bf16 v[64:79], v[160:163], v[168:171], v[64:79]
	v_mfma_f32_32x32x16_bf16 v[48:63], v[164:167], v[156:159], v[48:63]
	v_mfma_f32_32x32x16_bf16 v[32:47], v[160:163], v[156:159], v[32:47]
	v_mfma_f32_32x32x16_bf16 v[16:31], v[164:167], v[152:155], v[16:31]
	v_mfma_f32_32x32x16_bf16 v[0:15], v[160:163], v[152:155], v[0:15]
	s_add_i32 s8, s22, 0x6000
	s_cmpk_lg_u32 s22, 0xc000
	s_cselect_b32 s22, s8, 0
	s_add_i32 s1, s1, 1
	s_waitcnt vmcnt(0) lgkmcnt(0)
	s_barrier
	s_cmp_lg_u32 s1, 8
	s_cbranch_scc1 .Lgemm_g4_tail
	s_branch .LBB0_311

.LBB0_316:
	s_add_u32 s76, s76, 0x9508000
	s_addc_u32 s77, s77, 0
	s_add_u32 s4, s4, 0x37b0000
	s_addc_u32 s5, s5, 0
	v_mov_b32_e32 v128, 0
	v_mov_b32_e32 v129, 0
	v_mov_b32_e32 v130, 0
	v_mov_b32_e32 v131, 0
	v_mov_b32_e32 v132, 0
	v_mov_b32_e32 v133, 0
	v_mov_b32_e32 v134, 0
	v_mov_b32_e32 v135, 0
	v_mov_b32_e32 v136, 0
	v_mov_b32_e32 v137, 0
	v_mov_b32_e32 v138, 0
	v_mov_b32_e32 v139, 0
	v_mov_b32_e32 v140, 0
	v_mov_b32_e32 v141, 0
	v_mov_b32_e32 v142, 0
	v_mov_b32_e32 v143, 0
	v_mov_b32_e32 v144, 0
	v_mov_b32_e32 v145, 0
	v_mov_b32_e32 v146, 0
	v_mov_b32_e32 v147, 0
	v_mov_b32_e32 v148, 0
	v_mov_b32_e32 v149, 0
	v_mov_b32_e32 v150, 0
	v_mov_b32_e32 v151, 0
.Lgemm_g5_main:
	s_add_i32 s22, s11, 0
	v_add_u32_e32 v183, s22, v179
	v_add_u32_e32 v152, v183, v181
	ds_read_b128 v[172:175], v152
	ds_read_b128 v[168:171], v152 offset:2048
	ds_read_b128 v[156:159], v152 offset:4096
	ds_read_b128 v[152:155], v152 offset:6144
	v_add_u32_e32 v184, s22, v180
	v_add_u32_e32 v160, v184, v181
	ds_read_b128 v[164:167], v160 offset:16384
	ds_read_b128 v[160:163], v160 offset:18432
	s_add_i32 s6, s1, s10
	s_mov_b32 m0, s6
	v_mfma_f32_32x32x16_bf16 v[112:127], v[148:151], v[144:147], v[112:127]
	global_load_lds_dwordx4 v176, s[76:77]
	s_add_u32 s98, s76, 0x1000
	s_addc_u32 s99, s77, 0
	s_add_i32 m0, s6, 0x1000
	v_mfma_f32_32x32x16_bf16 v[96:111], v[132:135], v[144:147], v[96:111]
	v_mfma_f32_32x32x16_bf16 v[80:95], v[148:151], v[140:143], v[80:95]
	global_load_lds_dwordx4 v176, s[98:99]
	s_add_u32 s100, s76, 0x2000
	s_addc_u32 s101, s77, 0
	s_add_i32 m0, s6, 0x2000
	v_mfma_f32_32x32x16_bf16 v[64:79], v[132:135], v[140:143], v[64:79]
	v_mfma_f32_32x32x16_bf16 v[48:63], v[148:151], v[136:139], v[48:63]
	global_load_lds_dwordx4 v176, s[100:101]
	s_add_u32 s98, s76, 0x3000
	s_addc_u32 s99, s77, 0
	s_add_i32 m0, s6, 0x3000
	v_mfma_f32_32x32x16_bf16 v[32:47], v[132:135], v[136:139], v[32:47]
	v_mfma_f32_32x32x16_bf16 v[16:31], v[148:151], v[128:131], v[16:31]
	global_load_lds_dwordx4 v176, s[98:99]
	v_mfma_f32_32x32x16_bf16 v[0:15], v[132:135], v[128:131], v[0:15]
	v_add_u32_e32 v128, v183, v182
	ds_read_b128 v[144:147], v128
	ds_read_b128 v[140:143], v128 offset:2048
	ds_read_b128 v[136:139], v128 offset:4096
	ds_read_b128 v[128:131], v128 offset:6144
	v_add_u32_e32 v132, v184, v182
	ds_read_b128 v[148:151], v132 offset:16384
	ds_read_b128 v[132:135], v132 offset:18432
	s_add_i32 m0, s6, 0x4000
	s_add_u32 s100, s4, 0x1000
	s_addc_u32 s101, s5, 0
	s_waitcnt lgkmcnt(6)
	v_mfma_f32_32x32x16_bf16 v[112:127], v[164:167], v[172:175], v[112:127]
	global_load_lds_dwordx4 v176, s[4:5]
	s_add_i32 m0, s6, 0x5000
	v_mfma_f32_32x32x16_bf16 v[96:111], v[160:163], v[172:175], v[96:111]
	v_mfma_f32_32x32x16_bf16 v[80:95], v[164:167], v[168:171], v[80:95]
	global_load_lds_dwordx4 v176, s[100:101]
	v_mfma_f32_32x32x16_bf16 v[64:79], v[160:163], v[168:171], v[64:79]
	v_mfma_f32_32x32x16_bf16 v[48:63], v[164:167], v[156:159], v[48:63]
	v_mfma_f32_32x32x16_bf16 v[32:47], v[160:163], v[156:159], v[32:47]
	v_mfma_f32_32x32x16_bf16 v[16:31], v[164:167], v[152:155], v[16:31]
	v_mfma_f32_32x32x16_bf16 v[0:15], v[160:163], v[152:155], v[0:15]
	s_add_u32 s76, s76, 0x80000
	s_addc_u32 s77, s77, 0
	s_add_u32 s4, s4, 0x18000
	s_addc_u32 s5, s5, 0
	s_add_i32 s6, s10, 0x6000
	s_cmpk_lg_u32 s10, 0xc000
	s_cselect_b32 s10, s6, 0
	s_add_i32 s6, s11, 0x6000
	s_cmpk_lg_u32 s11, 0xc000
	s_cselect_b32 s11, s6, 0
	s_add_i32 s9, s9, 1
	s_waitcnt vmcnt(6) lgkmcnt(0)
	s_barrier
	s_cmp_lg_u32 s9, 14
	s_cbranch_scc1 .Lgemm_g5_main
.Lgemm_g5_tail:
	s_add_i32 s22, s11, 0
	v_add_u32_e32 v183, s22, v179
	v_add_u32_e32 v152, v183, v181
	ds_read_b128 v[172:175], v152
	ds_read_b128 v[168:171], v152 offset:2048
	ds_read_b128 v[156:159], v152 offset:4096
	ds_read_b128 v[152:155], v152 offset:6144
	v_add_u32_e32 v184, s22, v180
	v_add_u32_e32 v160, v184, v181
	ds_read_b128 v[164:167], v160 offset:16384
	ds_read_b128 v[160:163], v160 offset:18432
	v_mfma_f32_32x32x16_bf16 v[112:127], v[148:151], v[144:147], v[112:127]
	v_mfma_f32_32x32x16_bf16 v[96:111], v[132:135], v[144:147], v[96:111]
	v_mfma_f32_32x32x16_bf16 v[80:95], v[148:151], v[140:143], v[80:95]
	v_mfma_f32_32x32x16_bf16 v[64:79], v[132:135], v[140:143], v[64:79]
	v_mfma_f32_32x32x16_bf16 v[48:63], v[148:151], v[136:139], v[48:63]
	v_mfma_f32_32x32x16_bf16 v[32:47], v[132:135], v[136:139], v[32:47]
	v_mfma_f32_32x32x16_bf16 v[16:31], v[148:151], v[128:131], v[16:31]
	v_mfma_f32_32x32x16_bf16 v[0:15], v[132:135], v[128:131], v[0:15]
	v_add_u32_e32 v128, v183, v182
	ds_read_b128 v[144:147], v128
	ds_read_b128 v[140:143], v128 offset:2048
	ds_read_b128 v[136:139], v128 offset:4096
	ds_read_b128 v[128:131], v128 offset:6144
	v_add_u32_e32 v132, v184, v182
	ds_read_b128 v[148:151], v132 offset:16384
	ds_read_b128 v[132:135], v132 offset:18432
	s_waitcnt lgkmcnt(6)
	v_mfma_f32_32x32x16_bf16 v[112:127], v[164:167], v[172:175], v[112:127]
	v_mfma_f32_32x32x16_bf16 v[96:111], v[160:163], v[172:175], v[96:111]
	v_mfma_f32_32x32x16_bf16 v[80:95], v[164:167], v[168:171], v[80:95]
	v_mfma_f32_32x32x16_bf16 v[64:79], v[160:163], v[168:171], v[64:79]
	v_mfma_f32_32x32x16_bf16 v[48:63], v[164:167], v[156:159], v[48:63]
	v_mfma_f32_32x32x16_bf16 v[32:47], v[160:163], v[156:159], v[32:47]
	v_mfma_f32_32x32x16_bf16 v[16:31], v[164:167], v[152:155], v[16:31]
	v_mfma_f32_32x32x16_bf16 v[0:15], v[160:163], v[152:155], v[0:15]
	s_add_i32 s6, s11, 0x6000
	s_cmpk_lg_u32 s11, 0xc000
	s_cselect_b32 s11, s6, 0
	s_add_i32 s9, s9, 1
	s_waitcnt vmcnt(0) lgkmcnt(0)
	s_barrier
	s_cmp_lg_u32 s9, 16
	s_cbranch_scc1 .Lgemm_g5_tail
	s_branch .LBB0_324

.LBB0_534:
	s_add_u32 s54, s54, s22
	s_addc_u32 s55, s55, s23
	s_add_u32 s50, s50, s44
	s_addc_u32 s51, s51, s45
	v_mov_b32_e32 v128, 0
	v_mov_b32_e32 v129, 0
	v_mov_b32_e32 v130, 0
	v_mov_b32_e32 v131, 0
	v_mov_b32_e32 v132, 0
	v_mov_b32_e32 v133, 0
	v_mov_b32_e32 v134, 0
	v_mov_b32_e32 v135, 0
	v_mov_b32_e32 v136, 0
	v_mov_b32_e32 v137, 0
	v_mov_b32_e32 v138, 0
	v_mov_b32_e32 v139, 0
	v_mov_b32_e32 v140, 0
	v_mov_b32_e32 v141, 0
	v_mov_b32_e32 v142, 0
	v_mov_b32_e32 v143, 0
	v_mov_b32_e32 v144, 0
	v_mov_b32_e32 v145, 0
	v_mov_b32_e32 v146, 0
	v_mov_b32_e32 v147, 0
	v_mov_b32_e32 v148, 0
	v_mov_b32_e32 v149, 0
	v_mov_b32_e32 v150, 0
	v_mov_b32_e32 v151, 0
.Lgemm_g6_main:
	s_add_i32 s58, s76, 0
	v_add_u32_e32 v183, s58, v179
	v_add_u32_e32 v152, v183, v181
	ds_read_b128 v[172:175], v152
	ds_read_b128 v[168:171], v152 offset:2048
	ds_read_b128 v[156:159], v152 offset:4096
	ds_read_b128 v[152:155], v152 offset:6144
	v_add_u32_e32 v184, s58, v180
	v_add_u32_e32 v160, v184, v181
	ds_read_b128 v[164:167], v160 offset:16384
	ds_read_b128 v[160:163], v160 offset:18432
	s_add_i32 s56, s49, s75
	s_mov_b32 m0, s56
	v_mfma_f32_32x32x16_bf16 v[112:127], v[136:139], v[148:151], v[112:127]
	global_load_lds_dwordx4 v176, s[54:55]
	s_add_u32 s98, s54, 0x1000
	s_addc_u32 s99, s55, 0
	s_add_i32 m0, s56, 0x1000
	v_mfma_f32_32x32x16_bf16 v[96:111], v[128:131], v[148:151], v[96:111]
	v_mfma_f32_32x32x16_bf16 v[80:95], v[136:139], v[144:147], v[80:95]
	global_load_lds_dwordx4 v176, s[98:99]
	s_add_u32 s100, s54, 0x2000
	s_addc_u32 s101, s55, 0
	s_add_i32 m0, s56, 0x2000
	v_mfma_f32_32x32x16_bf16 v[64:79], v[128:131], v[144:147], v[64:79]
	v_mfma_f32_32x32x16_bf16 v[48:63], v[136:139], v[140:143], v[48:63]
	global_load_lds_dwordx4 v176, s[100:101]
	s_add_u32 s98, s54, 0x3000
	s_addc_u32 s99, s55, 0
	s_add_i32 m0, s56, 0x3000
	v_mfma_f32_32x32x16_bf16 v[32:47], v[128:131], v[140:143], v[32:47]
	v_mfma_f32_32x32x16_bf16 v[16:31], v[136:139], v[132:135], v[16:31]
	global_load_lds_dwordx4 v176, s[98:99]
	v_mfma_f32_32x32x16_bf16 v[0:15], v[128:131], v[132:135], v[0:15]
	v_add_u32_e32 v128, v183, v182
	ds_read_b128 v[148:151], v128
	ds_read_b128 v[144:147], v128 offset:2048
	ds_read_b128 v[140:143], v128 offset:4096
	ds_read_b128 v[132:135], v128 offset:6144
	v_add_u32_e32 v128, v184, v182
	ds_read_b128 v[136:139], v128 offset:16384
	ds_read_b128 v[128:131], v128 offset:18432
	s_add_i32 m0, s56, 0x4000
	s_add_u32 s100, s50, 0x1000
	s_addc_u32 s101, s51, 0
	s_waitcnt lgkmcnt(6)
	v_mfma_f32_32x32x16_bf16 v[112:127], v[164:167], v[172:175], v[112:127]
	global_load_lds_dwordx4 v176, s[50:51]
	s_add_i32 m0, s56, 0x5000
	v_mfma_f32_32x32x16_bf16 v[96:111], v[160:163], v[172:175], v[96:111]
	v_mfma_f32_32x32x16_bf16 v[80:95], v[164:167], v[168:171], v[80:95]
	global_load_lds_dwordx4 v176, s[100:101]
	v_mfma_f32_32x32x16_bf16 v[64:79], v[160:163], v[168:171], v[64:79]
	v_mfma_f32_32x32x16_bf16 v[48:63], v[164:167], v[156:159], v[48:63]
	v_mfma_f32_32x32x16_bf16 v[32:47], v[160:163], v[156:159], v[32:47]
	v_mfma_f32_32x32x16_bf16 v[16:31], v[164:167], v[152:155], v[16:31]
	v_mfma_f32_32x32x16_bf16 v[0:15], v[160:163], v[152:155], v[0:15]
	s_add_u32 s54, s54, 0x80000
	s_addc_u32 s55, s55, 0
	s_add_u32 s50, s50, 0x20000
	s_addc_u32 s51, s51, 0
	s_add_i32 s56, s75, 0x6000
	s_cmpk_lg_u32 s75, 0xc000
	s_cselect_b32 s75, s56, 0
	s_add_i32 s56, s76, 0x6000
	s_cmpk_lg_u32 s76, 0xc000
	s_cselect_b32 s76, s56, 0
	s_add_i32 s74, s74, 1
	s_waitcnt vmcnt(6) lgkmcnt(0)
	s_barrier
	s_cmp_lg_u32 s74, 62
	s_cbranch_scc1 .Lgemm_g6_main
.Lgemm_g6_tail:
	s_add_i32 s58, s76, 0
	v_add_u32_e32 v183, s58, v179
	v_add_u32_e32 v152, v183, v181
	ds_read_b128 v[172:175], v152
	ds_read_b128 v[168:171], v152 offset:2048
	ds_read_b128 v[156:159], v152 offset:4096
	ds_read_b128 v[152:155], v152 offset:6144
	v_add_u32_e32 v184, s58, v180
	v_add_u32_e32 v160, v184, v181
	ds_read_b128 v[164:167], v160 offset:16384
	ds_read_b128 v[160:163], v160 offset:18432
	v_mfma_f32_32x32x16_bf16 v[112:127], v[136:139], v[148:151], v[112:127]
	v_mfma_f32_32x32x16_bf16 v[96:111], v[128:131], v[148:151], v[96:111]
	v_mfma_f32_32x32x16_bf16 v[80:95], v[136:139], v[144:147], v[80:95]
	v_mfma_f32_32x32x16_bf16 v[64:79], v[128:131], v[144:147], v[64:79]
	v_mfma_f32_32x32x16_bf16 v[48:63], v[136:139], v[140:143], v[48:63]
	v_mfma_f32_32x32x16_bf16 v[32:47], v[128:131], v[140:143], v[32:47]
	v_mfma_f32_32x32x16_bf16 v[16:31], v[136:139], v[132:135], v[16:31]
	v_mfma_f32_32x32x16_bf16 v[0:15], v[128:131], v[132:135], v[0:15]
	v_add_u32_e32 v128, v183, v182
	ds_read_b128 v[148:151], v128
	ds_read_b128 v[144:147], v128 offset:2048
	ds_read_b128 v[140:143], v128 offset:4096
	ds_read_b128 v[132:135], v128 offset:6144
	v_add_u32_e32 v128, v184, v182
	ds_read_b128 v[136:139], v128 offset:16384
	ds_read_b128 v[128:131], v128 offset:18432
	s_waitcnt lgkmcnt(6)
	v_mfma_f32_32x32x16_bf16 v[112:127], v[164:167], v[172:175], v[112:127]
	v_mfma_f32_32x32x16_bf16 v[96:111], v[160:163], v[172:175], v[96:111]
	v_mfma_f32_32x32x16_bf16 v[80:95], v[164:167], v[168:171], v[80:95]
	v_mfma_f32_32x32x16_bf16 v[64:79], v[160:163], v[168:171], v[64:79]
	v_mfma_f32_32x32x16_bf16 v[48:63], v[164:167], v[156:159], v[48:63]
	v_mfma_f32_32x32x16_bf16 v[32:47], v[160:163], v[156:159], v[32:47]
	v_mfma_f32_32x32x16_bf16 v[16:31], v[164:167], v[152:155], v[16:31]
	v_mfma_f32_32x32x16_bf16 v[0:15], v[160:163], v[152:155], v[0:15]
	s_add_i32 s56, s76, 0x6000
	s_cmpk_lg_u32 s76, 0xc000
	s_cselect_b32 s76, s56, 0
	s_add_i32 s74, s74, 1
	s_waitcnt vmcnt(0) lgkmcnt(0)
	s_barrier
	s_cmp_lg_u32 s74, 64
	s_cbranch_scc1 .Lgemm_g6_tail
	s_branch .LBB0_542

	.amdhsa_kernel _Z14fwd_megakernel6Params
		.amdhsa_group_segment_fixed_size 0
		.amdhsa_private_segment_fixed_size 0
		.amdhsa_kernarg_size 352
		.amdhsa_user_sgpr_count 2
		.amdhsa_user_sgpr_dispatch_ptr 0
		.amdhsa_user_sgpr_queue_ptr 0
		.amdhsa_user_sgpr_kernarg_segment_ptr 1
		.amdhsa_user_sgpr_dispatch_id 0
		.amdhsa_user_sgpr_kernarg_preload_length 0
		.amdhsa_user_sgpr_kernarg_preload_offset 0
		.amdhsa_user_sgpr_private_segment_size 0
		.amdhsa_uses_dynamic_stack 0
		.amdhsa_enable_private_segment 0
		.amdhsa_system_sgpr_workgroup_id_x 1
		.amdhsa_system_sgpr_workgroup_id_y 0
		.amdhsa_system_sgpr_workgroup_id_z 0
		.amdhsa_system_sgpr_workgroup_info 0
		.amdhsa_system_vgpr_workitem_id 2
		.amdhsa_next_free_vgpr 256
		.amdhsa_next_free_sgpr 102
		.amdhsa_accum_offset 256
		.amdhsa_reserve_vcc 1
		.amdhsa_float_round_mode_32 0
		.amdhsa_float_round_mode_16_64 0
		.amdhsa_float_denorm_mode_32 3
		.amdhsa_float_denorm_mode_16_64 3
		.amdhsa_dx10_clamp 1
		.amdhsa_ieee_mode 1
		.amdhsa_fp16_overflow 0
		.amdhsa_tg_split 0
		.amdhsa_exception_fp_ieee_invalid_op 0
		.amdhsa_exception_fp_denorm_src 0
		.amdhsa_exception_fp_ieee_div_zero 0
		.amdhsa_exception_fp_ieee_overflow 0
		.amdhsa_exception_fp_ieee_underflow 0
		.amdhsa_exception_fp_ieee_inexact 0
		.amdhsa_exception_int_div_zero 0
	.end_amdhsa_kernel

amdhsa.kernels:
  - .agpr_count:     0
    .args:
      - .offset:         0
        .size:           96
        .value_kind:     by_value
      - .offset:         96
        .size:           4
        .value_kind:     hidden_block_count_x
      - .offset:         100
        .size:           4
        .value_kind:     hidden_block_count_y
      - .offset:         104
        .size:           4
        .value_kind:     hidden_block_count_z
      - .offset:         108
        .size:           2
        .value_kind:     hidden_group_size_x
      - .offset:         110
        .size:           2
        .value_kind:     hidden_group_size_y
      - .offset:         112
        .size:           2
        .value_kind:     hidden_group_size_z
      - .offset:         114
        .size:           2
        .value_kind:     hidden_remainder_x
      - .offset:         116
        .size:           2
        .value_kind:     hidden_remainder_y
      - .offset:         118
        .size:           2
        .value_kind:     hidden_remainder_z
      - .offset:         136
        .size:           8
        .value_kind:     hidden_global_offset_x
      - .offset:         144
        .size:           8
        .value_kind:     hidden_global_offset_y
      - .offset:         152
        .size:           8
        .value_kind:     hidden_global_offset_z
      - .offset:         160
        .size:           2
        .value_kind:     hidden_grid_dims
      - .offset:         184
        .size:           8
        .value_kind:     hidden_multigrid_sync_arg
      - .offset:         216
        .size:           4
        .value_kind:     hidden_dynamic_lds_size
    .group_segment_fixed_size: 0
    .kernarg_segment_align: 8
    .kernarg_segment_size: 352
    .language:       OpenCL C
    .language_version:
      - 2
      - 0
    .max_flat_workgroup_size: 256
    .name:           _Z14fwd_megakernel6Params
    .private_segment_fixed_size: 0
    .sgpr_count:     108
    .sgpr_spill_count: 33
    .symbol:         _Z14fwd_megakernel6Params.kd
    .uniform_work_group_size: 1
    .uses_dynamic_stack: false
    .vgpr_count:     256
    .vgpr_spill_count: 0
    .wavefront_size: 64
